# v17 + half-step-1 partialSM (max chain, rescale factor, 16 exp2) inside PV MFMA gaps on the unmasked path
# speedup vs baseline: 1.0015x; 1.0015x over previous
; __device__ __forceinline__ void finishSM(f32x16& p0, f32x16& p1, float alpha, float& l_reg, bf16x8& pa0, bf16x8& pa1, bf16x8& pa2, bf16x8& pa3) {
;     for (int r = 0; r < 16; ++r) p1[r] = __builtin_amdgcn_exp2f(p1[r]);
;     float ps = 0; for (int r = 0; r < 16; ++r) ps += p0[r]; for (int r = 0; r < 16; ++r) ps += p1[r];
;     { auto rr = __builtin_amdgcn_permlane32_swap(__float_as_uint(ps), __float_as_uint(ps), false, false);
;       ps = __uint_as_float(rr[0]) + __uint_as_float(rr[1]); }
;     l_reg = l_reg * alpha + ps;
;     ...
;     PK4(p0, 0, pa0); PK4(p0, 8, pa1); PK4(p1, 0, pa2); PK4(p1, 8, pa3);
;     ...
; }
; template <int KB>
; __device__ __forceinline__ void qkt(f32x16& p0, f32x16& p1, const char* K_lds, int r32, int hi, const bf16x8* qr) {
;     p0 = f32x16{}; p1 = f32x16{};
;     const char* kb[4];
; #pragma unroll
;     for (int dd = 0; dd < 4; ++dd) kb[dd] = K_lds + KB * SHM_K + KSWZ(r32, (dd * 16 + hi * 8) * 2);
; #pragma unroll
;     for (int d0 = 0; d0 < 8; ++d0) { const char* a = kb[d0 & 3] + (d0 >> 2) * 128;
;         bf16x8 b0 = *reinterpret_cast<const bf16x8*>(a);
;         bf16x8 b1 = *reinterpret_cast<const bf16x8*>(a + 32 * 256);
;         p0 = __builtin_amdgcn_mfma_f32_32x32x16_bf16(b0, qr[d0], p0, 0, 0, 0);
;         p1 = __builtin_amdgcn_mfma_f32_32x32x16_bf16(b1, qr[d0], p1, 0, 0, 0); }
; }
.LBB0_89:
	s_waitcnt vmcnt(0)
	ds_read_b128 v[66:69], v169 offset:49152
	ds_read_b128 v[70:73], v169 offset:57344
	ds_read_b128 v[100:103], v193 offset:49152
	ds_read_b128 v[136:139], v193 offset:57344
	s_waitcnt lgkmcnt(3)
	v_mfma_f32_32x32x16_bf16 v[82:97], v[66:69], v[132:135], 0
	v_add_f32_e32 v148, 0, v231
	v_add_f32_e32 v148, v233, v148
	v_add_f32_e32 v148, v229, v148
	v_add_f32_e32 v148, v232, v148
	v_add_f32_e32 v148, v228, v148
	s_waitcnt lgkmcnt(2)
	v_mfma_f32_32x32x16_bf16 v[66:81], v[70:73], v[132:135], 0
	v_add_f32_e32 v148, v230, v148
	v_add_f32_e32 v148, v226, v148
	v_add_f32_e32 v148, v227, v148
	v_add_f32_e32 v148, v223, v148
	v_add_f32_e32 v148, v225, v148
	s_waitcnt lgkmcnt(1)
	v_mfma_f32_32x32x16_bf16 v[82:97], v[100:103], v[128:131], v[82:97]
	v_add_f32_e32 v148, v209, v148
	v_add_f32_e32 v148, v224, v148
	v_add_f32_e32 v148, v206, v148
	v_add_f32_e32 v148, v208, v148
	v_add_f32_e32 v148, v205, v148
	s_waitcnt lgkmcnt(0)
	v_mfma_f32_32x32x16_bf16 v[66:81], v[136:139], v[128:131], v[66:81]
	v_add_f32_e32 v148, v207, v148
	v_exp_f32_e32 v140, v152
	v_exp_f32_e32 v141, v153
	v_exp_f32_e32 v142, v180
	v_exp_f32_e32 v143, v181
	ds_read_b128 v[100:103], v194 offset:49152
	ds_read_b128 v[136:139], v194 offset:57344
	s_waitcnt lgkmcnt(1)
	v_mfma_f32_32x32x16_bf16 v[82:97], v[100:103], v[124:127], v[82:97]
	v_exp_f32_e32 v144, v160
	v_exp_f32_e32 v145, v161
	v_exp_f32_e32 v146, v154
	v_exp_f32_e32 v147, v155
	v_exp_f32_e32 v234, v178
	s_waitcnt lgkmcnt(0)
	v_mfma_f32_32x32x16_bf16 v[66:81], v[136:139], v[124:127], v[66:81]
	v_exp_f32_e32 v235, v179
	v_exp_f32_e32 v236, v162
	v_exp_f32_e32 v237, v163
	v_add_f32_e32 v148, v234, v148
	v_add_f32_e32 v148, v235, v148
	ds_read_b128 v[100:103], v195 offset:49152
	ds_read_b128 v[136:139], v195 offset:57344
	s_waitcnt lgkmcnt(1)
	v_mfma_f32_32x32x16_bf16 v[82:97], v[100:103], v[120:123], v[82:97]
	v_add_f32_e32 v148, v236, v148
	v_exp_f32_e32 v238, v158
	v_exp_f32_e32 v239, v159
	v_exp_f32_e32 v240, v156
	v_exp_f32_e32 v241, v157
	s_waitcnt lgkmcnt(0)
	v_mfma_f32_32x32x16_bf16 v[66:81], v[136:139], v[120:123], v[66:81]
	v_add_f32_e32 v148, v237, v148
	v_add_f32_e32 v148, v238, v148
	v_add_f32_e32 v148, v239, v148
	v_add_f32_e32 v148, v240, v148
	v_add_f32_e32 v148, v241, v148
	ds_read_b128 v[100:103], v169 offset:49280
	ds_read_b128 v[136:139], v169 offset:57472
	s_waitcnt lgkmcnt(1)
	v_mfma_f32_32x32x16_bf16 v[82:97], v[100:103], v[116:119], v[82:97]
	v_add_f32_e32 v148, v140, v148
	v_add_f32_e32 v148, v141, v148
	v_add_f32_e32 v148, v142, v148
	v_add_f32_e32 v148, v143, v148
	v_add_f32_e32 v148, v144, v148
	s_waitcnt lgkmcnt(0)
	v_mfma_f32_32x32x16_bf16 v[66:81], v[136:139], v[116:119], v[66:81]
	v_add_f32_e32 v148, v145, v148
	v_add_f32_e32 v148, v146, v148
	v_add_f32_e32 v199, v147, v148
	v_mov_b32_e32 v200, v199
	s_nop 1
	v_permlane32_swap_b32_e32 v199, v200
	v_cvt_pk_bf16_f32 v148, v231, v233
	ds_read_b128 v[100:103], v193 offset:49280
	ds_read_b128 v[136:139], v193 offset:57472
	s_waitcnt lgkmcnt(1)
	v_mfma_f32_32x32x16_bf16 v[82:97], v[100:103], v[112:115], v[82:97]
	v_cvt_pk_bf16_f32 v149, v229, v232
	v_cvt_pk_bf16_f32 v150, v228, v230
	v_cvt_pk_bf16_f32 v151, v226, v227
	v_cvt_pk_bf16_f32 v152, v223, v225
	v_cvt_pk_bf16_f32 v153, v209, v224
	s_waitcnt lgkmcnt(0)
	v_mfma_f32_32x32x16_bf16 v[66:81], v[136:139], v[112:115], v[66:81]
	v_cvt_pk_bf16_f32 v154, v206, v208
	v_cvt_pk_bf16_f32 v155, v205, v207
	v_cvt_pk_bf16_f32 v156, v234, v235
	v_cvt_pk_bf16_f32 v157, v236, v237
	v_cvt_pk_bf16_f32 v158, v238, v239
	ds_read_b128 v[100:103], v194 offset:49280
	ds_read_b128 v[136:139], v194 offset:57472
	s_waitcnt lgkmcnt(1)
	v_mfma_f32_32x32x16_bf16 v[82:97], v[100:103], v[108:111], v[82:97]
	v_cvt_pk_bf16_f32 v159, v240, v241
	v_cvt_pk_bf16_f32 v160, v140, v141
	v_cvt_pk_bf16_f32 v161, v142, v143
	v_cvt_pk_bf16_f32 v162, v144, v145
	v_cvt_pk_bf16_f32 v163, v146, v147
	s_waitcnt lgkmcnt(0)
	v_mfma_f32_32x32x16_bf16 v[66:81], v[136:139], v[108:111], v[66:81]
	s_nop 0
	v_permlane32_swap_b32_e32 v148, v150
	v_permlane32_swap_b32_e32 v149, v151
	v_permlane32_swap_b32_e32 v152, v154
	v_permlane32_swap_b32_e32 v153, v155
	ds_read_b128 v[100:103], v195 offset:49280
	ds_read_b128 v[136:139], v195 offset:57472
	s_waitcnt lgkmcnt(1)
	v_mfma_f32_32x32x16_bf16 v[82:97], v[100:103], v[104:107], v[82:97]
	v_permlane32_swap_b32_e32 v156, v158
	v_permlane32_swap_b32_e32 v157, v159
	v_permlane32_swap_b32_e32 v160, v162
	v_permlane32_swap_b32_e32 v161, v163
	s_waitcnt lgkmcnt(0)
	v_mfma_f32_32x32x16_bf16 v[66:81], v[136:139], v[104:107], v[66:81]
	v_add_u32_e32 v178, s7, v166
	v_add_u32_e32 v100, 1, v178
	v_add_u32_e32 v102, 33, v178
	v_ashrrev_i32_e32 v101, 31, v100
	v_ashrrev_i32_e32 v103, 31, v102
	v_lshlrev_b64 v[140:141], 8, v[100:101]
	v_lshlrev_b64 v[142:143], 8, v[102:103]
	v_lshl_add_u64 v[100:101], v[170:171], 0, v[140:141]
	v_lshl_add_u64 v[136:137], v[170:171], 0, v[142:143]
	v_lshl_add_u64 v[140:141], v[176:177], 0, v[140:141]
	v_lshl_add_u64 v[144:145], v[176:177], 0, v[142:143]
	global_load_dwordx4 v[100:103], v[100:101], off
	s_nop 0
	global_load_dwordx4 v[136:139], v[136:137], off
	s_nop 0
	global_load_dwordx4 v[140:143], v[140:141], off
	s_nop 0
	global_load_dwordx4 v[144:147], v[144:145], off
	s_cmp_le_i32 s7, s6
	s_cbranch_scc0 .Lmy_hs1_slow
; __device__ __forceinline__ void partialSM(f32x16& p0, f32x16& p1, float& m_reg, float& mn, float& alpha, bool rs) {
;     float pmax = p0[0]; for (int r = 1; r < 16; ++r) pmax = fmaxf(pmax, p0[r]); for (int r = 0; r < 16; ++r) pmax = fmaxf(pmax, p1[r]);
;     if (!rs) pmax = -__builtin_inff();
;     { auto rr = __builtin_amdgcn_permlane32_swap(__float_as_uint(pmax), __float_as_uint(pmax), false, false);
;       pmax = fmaxf(__uint_as_float(rr[0]), __uint_as_float(rr[1])); }
;     constexpr float C2 = 1.4426950408889634f * SCALE;
;     if (__builtin_expect(__all((pmax - m_reg) * SCALE <= THR), 1)) { mn = m_reg; alpha = 1.f; }
;     else { mn = fmaxf(m_reg, pmax); alpha = __builtin_amdgcn_exp2f((m_reg - mn) * C2); m_reg = mn; }
;     const float mnL = rs ? -mn * C2 : -__builtin_inff();
;     for (int r = 0; r < 16; ++r) p0[r] = fmaf(p0[r], C2, mnL); for (int r = 0; r < 16; ++r) p1[r] = fmaf(p1[r], C2, mnL);
;     for (int r = 0; r < 16; ++r) p0[r] = __builtin_amdgcn_exp2f(p0[r]);
; template <int VB>
; __device__ __forceinline__ void pv_tile(f32x16* o, int vb0, bf16x8 pa0, bf16x8 pa1, bf16x8 pa2, bf16x8 pa3) {
;     ...
;     PV_D0(0); PV_D0(1); PV_D0(2); PV_D0(3);
	ds_read_b64_tr_b16 v[172:173], v185 offset:0
	ds_read_b64_tr_b16 v[174:175], v185 offset:0x800
	ds_read_b64_tr_b16 v[202:203], v185 offset:0x1000
	ds_read_b64_tr_b16 v[204:205], v185 offset:0x1800
	ds_read_b64_tr_b16 v[206:207], v185 offset:0x2000
	ds_read_b64_tr_b16 v[208:209], v185 offset:0x2800
	ds_read_b64_tr_b16 v[224:225], v185 offset:0x3000
	ds_read_b64_tr_b16 v[226:227], v185 offset:0x3800
	s_waitcnt lgkmcnt(0)
	s_nop 0
	v_mfma_f32_32x32x16_bf16 v[50:65], v[148:151], v[172:175], v[50:65]
	ds_read_b64_tr_b16 v[172:173], v185 offset:0x200
	ds_read_b64_tr_b16 v[174:175], v185 offset:0xa00
	v_mfma_f32_32x32x16_bf16 v[50:65], v[152:155], v[202:205], v[50:65]
	s_add_i32 s0, s3, -2
	s_lshr_b32 s8, s0, 2
	s_cmp_ge_i32 s8, s44
	s_cselect_b64 s[0:1], -1, 0
	s_lshl_b32 s8, 1, s8
	v_and_b32_e32 v250, s8, v165
	ds_read_b64_tr_b16 v[202:203], v185 offset:0x1200
	ds_read_b64_tr_b16 v[204:205], v185 offset:0x1a00
	v_mfma_f32_32x32x16_bf16 v[50:65], v[156:159], v[206:209], v[50:65]
	v_cmp_ne_u32_e32 vcc, 0, v250
	v_max_f32_e32 v250, v83, v83
	v_max_f32_e32 v251, v82, v82
	v_max_f32_e32 v250, v251, v250
	v_max3_f32 v250, v250, v84, v85
	ds_read_b64_tr_b16 v[206:207], v185 offset:0x2200
	ds_read_b64_tr_b16 v[208:209], v185 offset:0x2a00
	v_mfma_f32_32x32x16_bf16 v[50:65], v[160:163], v[224:227], v[50:65]
	v_max3_f32 v250, v250, v86, v87
	v_max3_f32 v250, v250, v88, v89
	v_max3_f32 v250, v250, v90, v91
	v_max3_f32 v250, v250, v92, v93
	v_max3_f32 v250, v250, v94, v95
	ds_read_b64_tr_b16 v[224:225], v185 offset:0x3200
	ds_read_b64_tr_b16 v[226:227], v185 offset:0x3a00
	s_waitcnt lgkmcnt(0)
	v_mfma_f32_32x32x16_bf16 v[34:49], v[148:151], v[172:175], v[34:49]
	v_max3_f32 v250, v250, v96, v97
	v_max3_f32 v250, v250, v66, v67
	v_max3_f32 v250, v250, v68, v69
	v_max3_f32 v250, v250, v70, v71
	v_max3_f32 v250, v250, v72, v73
	ds_read_b64_tr_b16 v[172:173], v185 offset:0x400
	ds_read_b64_tr_b16 v[174:175], v185 offset:0xc00
	v_mfma_f32_32x32x16_bf16 v[34:49], v[152:155], v[202:205], v[34:49]
	v_max3_f32 v250, v250, v74, v75
	v_max3_f32 v250, v250, v76, v77
	v_max3_f32 v250, v250, v78, v79
	s_or_b64 s[40:41], s[0:1], vcc
	v_max3_f32 v250, v250, v80, v81
	ds_read_b64_tr_b16 v[202:203], v185 offset:0x1400
	ds_read_b64_tr_b16 v[204:205], v185 offset:0x1c00
	v_mfma_f32_32x32x16_bf16 v[34:49], v[156:159], v[206:209], v[34:49]
	v_cndmask_b32_e64 v250, v220, v250, s[40:41]
	v_mov_b32_e32 v251, v250
	s_nop 1
	v_permlane32_swap_b32_e32 v250, v251
	v_max_f32_e32 v251, v251, v251
	v_max_f32_e32 v250, v250, v250
	v_max_f32_e32 v250, v250, v251
	ds_read_b64_tr_b16 v[206:207], v185 offset:0x2400
	ds_read_b64_tr_b16 v[208:209], v185 offset:0x2c00
	v_mfma_f32_32x32x16_bf16 v[34:49], v[160:163], v[224:227], v[34:49]
	v_sub_f32_e32 v251, v250, v198
	v_mul_f32_e32 v251, 0x3db504f3, v251
	v_cmp_ge_f32_e32 vcc, s91, v251
	v_max_f32_e32 v251, v198, v198
	v_max_f32_e32 v250, v251, v250
	ds_read_b64_tr_b16 v[224:225], v185 offset:0x3400
	ds_read_b64_tr_b16 v[226:227], v185 offset:0x3c00
	s_waitcnt lgkmcnt(0)
	v_mfma_f32_32x32x16_bf16 v[18:33], v[148:151], v[172:175], v[18:33]
	v_sub_f32_e32 v251, v198, v250
	v_mul_f32_e32 v251, 0x3e0293ee, v251
	v_exp_f32_e32 v251, v251
	s_cmp_eq_u64 vcc, exec
	s_cselect_b64 s[42:43], -1, 0
	v_cndmask_b32_e64 v179, v250, v198, s[42:43]
	ds_read_b64_tr_b16 v[172:173], v185 offset:0x600
	ds_read_b64_tr_b16 v[174:175], v185 offset:0xe00
	v_mfma_f32_32x32x16_bf16 v[18:33], v[152:155], v[202:205], v[18:33]
	v_mul_f32_e32 v222, 0xbe0293ee, v179
	v_cndmask_b32_e64 v180, v220, v222, s[40:41]
	v_fmamk_f32 v82, v82, 0x3e0293ee, v180
	v_fmamk_f32 v83, v83, 0x3e0293ee, v180
	v_fmamk_f32 v84, v84, 0x3e0293ee, v180
	ds_read_b64_tr_b16 v[202:203], v185 offset:0x1600
	ds_read_b64_tr_b16 v[204:205], v185 offset:0x1e00
	v_mfma_f32_32x32x16_bf16 v[18:33], v[156:159], v[206:209], v[18:33]
	v_fmamk_f32 v85, v85, 0x3e0293ee, v180
	v_fmamk_f32 v86, v86, 0x3e0293ee, v180
	v_fmamk_f32 v87, v87, 0x3e0293ee, v180
	v_fmamk_f32 v88, v88, 0x3e0293ee, v180
	v_fmamk_f32 v89, v89, 0x3e0293ee, v180
	ds_read_b64_tr_b16 v[206:207], v185 offset:0x2600
	ds_read_b64_tr_b16 v[208:209], v185 offset:0x2e00
	v_mfma_f32_32x32x16_bf16 v[18:33], v[160:163], v[224:227], v[18:33]
	v_fmamk_f32 v90, v90, 0x3e0293ee, v180
	v_fmamk_f32 v91, v91, 0x3e0293ee, v180
	v_fmamk_f32 v92, v92, 0x3e0293ee, v180
	v_fmamk_f32 v93, v93, 0x3e0293ee, v180
	v_fmamk_f32 v94, v94, 0x3e0293ee, v180
	ds_read_b64_tr_b16 v[224:225], v185 offset:0x3600
	ds_read_b64_tr_b16 v[226:227], v185 offset:0x3e00
	s_waitcnt lgkmcnt(0)
	v_mfma_f32_32x32x16_bf16 v[2:17], v[148:151], v[172:175], v[2:17]
	v_fmamk_f32 v95, v95, 0x3e0293ee, v180
	v_fmamk_f32 v96, v96, 0x3e0293ee, v180
	v_fmamk_f32 v97, v97, 0x3e0293ee, v180
	v_exp_f32_e32 v234, v82
	v_exp_f32_e32 v249, v83
	v_mfma_f32_32x32x16_bf16 v[2:17], v[152:155], v[202:205], v[2:17]
	v_exp_f32_e32 v235, v84
	v_exp_f32_e32 v248, v85
	v_exp_f32_e32 v236, v86
	v_exp_f32_e32 v247, v87
	v_exp_f32_e32 v237, v88
	v_mfma_f32_32x32x16_bf16 v[2:17], v[156:159], v[206:209], v[2:17]
	v_exp_f32_e32 v246, v89
	v_exp_f32_e32 v238, v90
	v_exp_f32_e32 v245, v91
	v_exp_f32_e32 v239, v92
	v_exp_f32_e32 v244, v93
	v_mfma_f32_32x32x16_bf16 v[2:17], v[160:163], v[224:227], v[2:17]
	v_exp_f32_e32 v240, v94
	v_exp_f32_e32 v243, v95
	v_exp_f32_e32 v241, v96
	v_exp_f32_e32 v242, v97
	v_mov_b32_e32 v149, v251
	s_mov_b32 s100, 1
	s_branch .Lmy_hs1_b1

; __device__ __forceinline__ void finishSM(f32x16& p0, f32x16& p1, float alpha, float& l_reg, bf16x8& pa0, bf16x8& pa1, bf16x8& pa2, bf16x8& pa3) {
;     for (int r = 0; r < 16; ++r) p1[r] = __builtin_amdgcn_exp2f(p1[r]);
;     float ps = 0; for (int r = 0; r < 16; ++r) ps += p0[r]; for (int r = 0; r < 16; ++r) ps += p1[r];
;     { auto rr = __builtin_amdgcn_permlane32_swap(__float_as_uint(ps), __float_as_uint(ps), false, false);
;       ps = __uint_as_float(rr[0]) + __uint_as_float(rr[1]); }
;     l_reg = l_reg * alpha + ps;
;     ...
;     PK4(p0, 0, pa0); PK4(p0, 8, pa1); PK4(p1, 0, pa2); PK4(p1, 8, pa3);
;     ...
; }
; template <int KB>
; __device__ __forceinline__ void qkt(f32x16& p0, f32x16& p1, const char* K_lds, int r32, int hi, const bf16x8* qr) {
;     p0 = f32x16{}; p1 = f32x16{};
;     const char* kb[4];
; #pragma unroll
;     for (int dd = 0; dd < 4; ++dd) kb[dd] = K_lds + KB * SHM_K + KSWZ(r32, (dd * 16 + hi * 8) * 2);
; #pragma unroll
;     for (int d0 = 0; d0 < 8; ++d0) { const char* a = kb[d0 & 3] + (d0 >> 2) * 128;
;         bf16x8 b0 = *reinterpret_cast<const bf16x8*>(a);
;         bf16x8 b1 = *reinterpret_cast<const bf16x8*>(a + 32 * 256);
;         p0 = __builtin_amdgcn_mfma_f32_32x32x16_bf16(b0, qr[d0], p0, 0, 0, 0);
;         p1 = __builtin_amdgcn_mfma_f32_32x32x16_bf16(b1, qr[d0], p1, 0, 0, 0); }
; }
.Lmy_hs1_p1:
	v_fmamk_f32 v203, v73, 0x3e0293ee, v180
	v_fmamk_f32 v204, v74, 0x3e0293ee, v180
	v_fmamk_f32 v208, v66, 0x3e0293ee, v180
	v_fmamk_f32 v209, v67, 0x3e0293ee, v180
	v_fmamk_f32 v223, v68, 0x3e0293ee, v180
	v_fmamk_f32 v224, v69, 0x3e0293ee, v180
	v_fmamk_f32 v225, v70, 0x3e0293ee, v180
	v_fmamk_f32 v198, v71, 0x3e0293ee, v180
	v_fmamk_f32 v201, v72, 0x3e0293ee, v180
	v_fmamk_f32 v205, v75, 0x3e0293ee, v180
	v_fmamk_f32 v206, v76, 0x3e0293ee, v180
	v_fmamk_f32 v207, v77, 0x3e0293ee, v180
	v_fmamk_f32 v181, v78, 0x3e0293ee, v180
	v_fmamk_f32 v226, v79, 0x3e0293ee, v180
	v_fmamk_f32 v227, v80, 0x3e0293ee, v180
	v_fmac_f32_e32 v180, 0x3e0293ee, v81
	s_waitcnt lgkmcnt(0)
	s_barrier
	s_waitcnt vmcnt(0)
	ds_read_b128 v[66:69], v169 offset:32768
	ds_read_b128 v[70:73], v169 offset:40960
	ds_read_b128 v[172:175], v193 offset:32768
	ds_read_b128 v[228:231], v193 offset:40960
	s_waitcnt lgkmcnt(3)
	v_mfma_f32_32x32x16_bf16 v[82:97], v[66:69], v[132:135], 0
	v_exp_f32_e32 v198, v198
	v_exp_f32_e32 v201, v201
	v_exp_f32_e32 v214, v204
	v_exp_f32_e32 v205, v205
	v_exp_f32_e32 v206, v206
	s_waitcnt lgkmcnt(2)
	v_mfma_f32_32x32x16_bf16 v[66:81], v[70:73], v[132:135], 0
	v_exp_f32_e32 v207, v207
	v_exp_f32_e32 v181, v181
	v_exp_f32_e32 v215, v226
	v_exp_f32_e32 v216, v227
	v_exp_f32_e32 v180, v180
	s_waitcnt lgkmcnt(1)
	v_mfma_f32_32x32x16_bf16 v[82:97], v[172:175], v[128:131], v[82:97]
	v_exp_f32_e32 v218, v209
	v_exp_f32_e32 v209, v203
	v_add_f32_e32 v203, 0, v234
	v_add_f32_e32 v203, v249, v203
	v_add_f32_e32 v203, v235, v203
	s_waitcnt lgkmcnt(0)
	v_mfma_f32_32x32x16_bf16 v[66:81], v[228:231], v[128:131], v[66:81]
	v_add_f32_e32 v203, v248, v203
	v_add_f32_e32 v203, v236, v203
	v_add_f32_e32 v203, v247, v203
	v_add_f32_e32 v203, v237, v203
	v_add_f32_e32 v203, v246, v203
	ds_read_b128 v[172:175], v194 offset:32768
	ds_read_b128 v[228:231], v194 offset:40960
	s_waitcnt lgkmcnt(1)
	v_mfma_f32_32x32x16_bf16 v[82:97], v[172:175], v[124:127], v[82:97]
	v_add_f32_e32 v203, v238, v203
	v_add_f32_e32 v203, v245, v203
	v_add_f32_e32 v203, v239, v203
	v_add_f32_e32 v203, v244, v203
	v_exp_f32_e32 v217, v208
	s_waitcnt lgkmcnt(0)
	v_mfma_f32_32x32x16_bf16 v[66:81], v[228:231], v[124:127], v[66:81]
	v_add_f32_e32 v203, v240, v203
	v_add_f32_e32 v203, v243, v203
	v_exp_f32_e32 v219, v223
	v_add_f32_e32 v203, v241, v203
	v_exp_f32_e32 v222, v224
	ds_read_b128 v[172:175], v195 offset:32768
	ds_read_b128 v[228:231], v195 offset:40960
	s_waitcnt lgkmcnt(1)
	v_mfma_f32_32x32x16_bf16 v[82:97], v[172:175], v[120:123], v[82:97]
	v_add_f32_e32 v203, v242, v203
	v_exp_f32_e32 v208, v225
	v_add_f32_e32 v203, v217, v203
	v_add_f32_e32 v203, v218, v203
	v_add_f32_e32 v203, v219, v203
	s_waitcnt lgkmcnt(0)
	v_mfma_f32_32x32x16_bf16 v[66:81], v[228:231], v[120:123], v[66:81]
	v_add_f32_e32 v203, v222, v203
	v_add_f32_e32 v203, v208, v203
	v_add_f32_e32 v203, v198, v203
	v_add_f32_e32 v203, v201, v203
	v_add_f32_e32 v203, v209, v203
	ds_read_b128 v[172:175], v169 offset:32896
	ds_read_b128 v[228:231], v169 offset:41088
	s_waitcnt lgkmcnt(1)
	v_mfma_f32_32x32x16_bf16 v[82:97], v[172:175], v[116:119], v[82:97]
	v_add_f32_e32 v203, v214, v203
	v_add_f32_e32 v203, v205, v203
	v_add_f32_e32 v203, v206, v203
	v_add_f32_e32 v203, v207, v203
	v_add_f32_e32 v203, v181, v203
	s_waitcnt lgkmcnt(0)
	v_mfma_f32_32x32x16_bf16 v[66:81], v[228:231], v[116:119], v[66:81]
	v_add_f32_e32 v203, v215, v203
	v_add_f32_e32 v203, v216, v203
	v_add_f32_e32 v203, v180, v203
	v_mov_b32_e32 v204, v203
	v_cvt_pk_bf16_f32 v148, v234, v249
	ds_read_b128 v[172:175], v193 offset:32896
	ds_read_b128 v[228:231], v193 offset:41088
	s_waitcnt lgkmcnt(1)
	v_mfma_f32_32x32x16_bf16 v[82:97], v[172:175], v[112:115], v[82:97]
	v_cvt_pk_bf16_f32 v149, v235, v248
	v_cvt_pk_bf16_f32 v150, v236, v247
	v_cvt_pk_bf16_f32 v151, v237, v246
	v_cvt_pk_bf16_f32 v152, v238, v245
	v_cvt_pk_bf16_f32 v153, v239, v244
	s_waitcnt lgkmcnt(0)
	v_mfma_f32_32x32x16_bf16 v[66:81], v[228:231], v[112:115], v[66:81]
	v_cvt_pk_bf16_f32 v154, v240, v243
	v_cvt_pk_bf16_f32 v155, v241, v242
	v_cvt_pk_bf16_f32 v156, v217, v218
	v_cvt_pk_bf16_f32 v157, v219, v222
	v_cvt_pk_bf16_f32 v158, v208, v198
	ds_read_b128 v[172:175], v194 offset:32896
	ds_read_b128 v[228:231], v194 offset:41088
	s_waitcnt lgkmcnt(1)
	v_mfma_f32_32x32x16_bf16 v[82:97], v[172:175], v[108:111], v[82:97]
	v_cvt_pk_bf16_f32 v159, v201, v209
	v_cvt_pk_bf16_f32 v160, v214, v205
	v_cvt_pk_bf16_f32 v161, v206, v207
	v_cvt_pk_bf16_f32 v162, v181, v215
	v_cvt_pk_bf16_f32 v163, v216, v180
	s_waitcnt lgkmcnt(0)
	v_mfma_f32_32x32x16_bf16 v[66:81], v[228:231], v[108:111], v[66:81]
	s_nop 1
	v_permlane32_swap_b32_e32 v203, v204
	v_permlane32_swap_b32_e32 v148, v150
	v_permlane32_swap_b32_e32 v149, v151
	v_permlane32_swap_b32_e32 v152, v154
	v_permlane32_swap_b32_e32 v153, v155
	ds_read_b128 v[172:175], v195 offset:32896
	ds_read_b128 v[228:231], v195 offset:41088
	s_waitcnt lgkmcnt(1)
	v_mfma_f32_32x32x16_bf16 v[82:97], v[172:175], v[104:107], v[82:97]
	v_permlane32_swap_b32_e32 v156, v158
	v_permlane32_swap_b32_e32 v157, v159
	v_permlane32_swap_b32_e32 v160, v162
	v_permlane32_swap_b32_e32 v161, v163
	s_waitcnt lgkmcnt(0)
	v_mfma_f32_32x32x16_bf16 v[66:81], v[228:231], v[104:107], v[66:81]
	s_cmp_lt_u32 s3, s2
	s_cselect_b64 s[22:23], -1, 0
	s_cmp_ge_u32 s3, s2
	s_cbranch_scc1 .LBB0_97
	v_add_u32_e32 v100, 0x41, v178
	v_add_u32_e32 v102, 0x61, v178
	v_ashrrev_i32_e32 v101, 31, v100
	v_ashrrev_i32_e32 v103, 31, v102
	v_lshlrev_b64 v[140:141], 8, v[100:101]
	v_lshlrev_b64 v[142:143], 8, v[102:103]
	v_lshl_add_u64 v[100:101], v[170:171], 0, v[140:141]
	v_lshl_add_u64 v[136:137], v[170:171], 0, v[142:143]
	v_lshl_add_u64 v[140:141], v[176:177], 0, v[140:141]
	v_lshl_add_u64 v[144:145], v[176:177], 0, v[142:143]
	global_load_dwordx4 v[100:103], v[100:101], off
	s_nop 0
	global_load_dwordx4 v[136:139], v[136:137], off
	s_nop 0
	global_load_dwordx4 v[140:143], v[140:141], off
	s_nop 0
	global_load_dwordx4 v[144:147], v[144:145], off
